# attA: QK as two 4-MFMA chains with score-independent VALU and the first chain's row max in the MFMA shadows; tile B LDS addresses as offset immediates; float tile index register; running max ping-pong
# speedup vs baseline: 1.0049x; 1.0049x over previous
; #define LAS __attribute__((address_space(3)))
; __device__ __forceinline__ float ex2(float v) { return __builtin_amdgcn_exp2f(v); }
; __device__ __forceinline__ void unit(LAS unsigned char* lds, bf16_t* P1, const bf16_t* vaT, int b, int h, int qblk, float lam, const float* subln_w, const float* khalf) {
;     ...
;     const float sl2 = ex2(-(float)(h + 1)) * LOG2E;
;     const float sl2h = sl2 * (float)(4 * hi);
;     float qbound;
;     { float q2 = 0.f;
; #pragma unroll
;       for (int ks = 0; ks < 4; ++ks)
; #pragma unroll
;           for (int e = 0; e < 8; ++e) { const float v = __uint_as_float((unsigned)(unsigned short)qf[ks][e] << 16); q2 += v * v; }
;       q2 += __shfl_xor(q2, 32);
;       const float* kh = khalf + (b * 16 + 2 * h + mi) * 2;
;       qbound = sqrtf(q2 * (kh[0] + kh[1])) * 1.01f + 0.05f; }
;     volatile LAS int* dflag = (volatile LAS int*)(lds + 4 * STG);
;     f32x16 O[4];
; #pragma unroll
;     for (int d = 0; d < 4; ++d)
; #pragma unroll
;         for (int r = 0; r < 16; ++r) O[d][r] = 0.f;
;     float m = -INFINITY, l = 0.f;
;     const int NT = 2 * qblk + 2;
;     const char* kbase = (const char*)(P1 + rowbase * LDP + C_KA + h * 128);
;     const char* vbase = (const char*)(vaT + (size_t)(h * 128) * MTOK + rowbase);
;     unsigned kso0, kso1, vso0, vso1;
;     { const int rk0 = (2 * wid) * 4 + (lane >> 4), rk1 = rk0 + 4, sl = lane & 15;
;       kso0 = (unsigned)((rk0 * LDP + ((sl ^ (rk0 & 15)) * 8)) * 2); kso1 = (unsigned)((rk1 * LDP + ((sl ^ (rk1 & 15)) * 8)) * 2);
;       const int d0 = (2 * wid) * 8 + (lane >> 3), d1 = d0 + 8, sv = lane & 7;
;       vso0 = (unsigned)((d0 * MTOK + ((sv ^ ((d0 >> 1) & 7)) * 8)) * 2); vso1 = (unsigned)((d1 * MTOK + ((sv ^ ((d1 >> 1) & 7)) * 8)) * 2); }
;     ...
;     unsigned koff[4], voff[4];
; #pragma unroll
;     for (int ks = 0; ks < 4; ++ks) koff[ks] = (unsigned)(r32 * 256 + (((mi * 8 + 2 * ks + hi) ^ (r32 & 15)) * 16));
; #pragma unroll
;     for (int q = 0; q < 4; ++q) voff[q] = (unsigned)(VOFF + r32 * 128 + (((2 * q + hi) ^ ((r32 >> 1) & 7)) * 16));
;     DMA_TILE(NT - 1, 0); DMA_TILE(NT - 2, 1); if (NT > 2) DMA_TILE(NT - 3, 2);
;     int stg = 0;
; #pragma unroll 1
;     for (int jj = 0; jj < NT; ++jj) {
;         const int j = NT - 1 - jj;
;         { const bool done = __all(qbound + sl2 * (float)(64 * j + 63 - qrow) < m - 24.f);
;           if (lane == 0) dflag[(jj & 1) * 8 + wid] = done ? 1 : 0; }
.LBB0_397:
	s_add_i32 s2, s4, 1
	v_cvt_f32_u32_e32 v0, s2
	s_waitcnt lgkmcnt(0)
	v_add_f32_e32 v4, v13, v14
	v_add_f32_e32 v2, v2, v3
	v_mul_f32_e32 v2, v2, v4
	s_mov_b32 s2, 0xf800000
	v_mul_f32_e32 v3, 0x4f800000, v2
	v_cmp_gt_f32_e32 vcc, s2, v2
	v_exp_f32_e64 v0, -v0
	s_add_i32 s73, s71, 2
	v_cndmask_b32_e32 v2, v2, v3, vcc
	v_sqrt_f32_e32 v3, v2
	v_mul_f32_e32 v127, 0x3fb8aa3b, v0
	s_add_i32 s75, s71, 1
	v_mov_b32_e32 v14, v1
	v_add_u32_e32 v0, -1, v3
	v_fma_f32 v4, -v0, v3, v2
	v_cmp_ge_f32_e64 s[2:3], 0, v4
	v_add_u32_e32 v4, 1, v3
	v_mov_b32_e32 v15, v1
	v_cndmask_b32_e64 v0, v3, v0, s[2:3]
	v_fma_f32 v3, -v4, v3, v2
	v_cmp_lt_f32_e64 s[2:3], 0, v3
	v_mov_b32_e32 v5, v1
	v_mov_b32_e32 v6, v1
	v_cndmask_b32_e64 v0, v0, v4, s[2:3]
	v_mul_f32_e32 v3, 0x37800000, v0
	v_cndmask_b32_e32 v0, v0, v3, vcc
	v_cmp_class_f32_e32 vcc, v2, v178
	s_lshl_b32 s2, s70, 3
	v_bitop3_b32 v3, s2, v148, v144 bitop3:0x36
	v_cndmask_b32_e32 v0, v0, v2, vcc
	v_or_b32_e32 v2, s2, v144
	s_lshl_b32 s2, s77, 2
	s_add_i32 s74, s2, 0
	s_add_i32 s74, s74, 0x20000
	s_lshl_b32 s2, s77, 19
	s_add_u32 s3, s44, s81
	s_addc_u32 s44, s45, 0
	s_andn2_b32 s5, 31, s5
	s_lshl_b32 s45, s5, 8
	s_add_u32 s3, s3, s45
	s_addc_u32 s45, s44, 0
	s_add_u32 s44, s66, s3
	s_addc_u32 s45, s67, s45
	s_mul_i32 s5, s5, 0x1a0000
	v_fmamk_f32 v132, v0, 0x3f8147ae, v179
	v_or_b32_e32 v0, s2, v172
	s_add_u32 s80, s80, s5
	s_mov_b32 s5, s11
	v_lshl_add_u64 v[134:135], v[0:1], 0, s[20:21]
	v_or_b32_e32 v0, s2, v173
	s_addc_u32 s81, 0, 0
	s_lshl_b64 s[2:3], s[4:5], 8
	s_add_u32 s2, s80, s2
	v_add_u32_e32 v0, v0, v12
	s_addc_u32 s3, s81, s3
	s_mul_i32 s4, s77, 0xd000
	v_lshl_add_u64 v[136:137], v[0:1], 0, s[20:21]
	v_add_u32_e32 v0, s4, v174
	s_add_u32 s2, s48, s2
	v_lshlrev_b32_e32 v129, 4, v3
	v_bitop3_b32 v3, v2, v148, 2 bitop3:0x36
	v_add_lshl_u32 v0, v0, v10, 1
	s_addc_u32 s3, s49, s3
	s_mul_i32 s77, s77, 0x1a000
	v_lshlrev_b32_e32 v185, 4, v3
	v_bitop3_b32 v3, v2, v148, 4 bitop3:0x36
	v_bitop3_b32 v2, v2, v148, 6 bitop3:0x36
	v_lshl_add_u64 v[138:139], s[2:3], 0, v[0:1]
	v_add3_u32 v0, v175, s77, v11
	v_lshlrev_b32_e32 v186, 4, v3
	v_lshlrev_b32_e32 v187, 4, v2
	v_lshl_add_u64 v[140:141], s[2:3], 0, v[0:1]
	v_mov_b32_e32 v0, v1
	v_mov_b32_e32 v2, v1
	v_mov_b32_e32 v3, v1
	v_mov_b32_e32 v4, v1
	v_mov_b32_e32 v7, v1
	v_mov_b32_e32 v8, v1
	v_mov_b32_e32 v9, v1
	v_mov_b32_e32 v10, v1
	v_mov_b32_e32 v11, v1
	v_mov_b32_e32 v12, v1
	v_mov_b32_e32 v13, v1
	v_mov_b64_e32 v[64:65], v[14:15]
	v_mov_b64_e32 v[48:49], v[14:15]
	v_mov_b64_e32 v[32:33], v[14:15]
	v_mul_f32_e32 v130, v127, v146
	v_mov_b64_e32 v[62:63], v[12:13]
	v_mov_b64_e32 v[60:61], v[10:11]
	v_mov_b64_e32 v[58:59], v[8:9]
	v_mov_b64_e32 v[56:57], v[6:7]
	v_mov_b64_e32 v[54:55], v[4:5]
	v_mov_b64_e32 v[52:53], v[2:3]
	v_mov_b64_e32 v[50:51], v[0:1]
	v_mov_b64_e32 v[46:47], v[12:13]
	v_mov_b64_e32 v[44:45], v[10:11]
	v_mov_b64_e32 v[42:43], v[8:9]
	v_mov_b64_e32 v[40:41], v[6:7]
	v_mov_b64_e32 v[38:39], v[4:5]
	v_mov_b64_e32 v[36:37], v[2:3]
	v_mov_b64_e32 v[34:35], v[0:1]
	v_mov_b64_e32 v[30:31], v[12:13]
	v_mov_b64_e32 v[28:29], v[10:11]
	v_mov_b64_e32 v[26:27], v[8:9]
	v_mov_b64_e32 v[24:25], v[6:7]
	v_mov_b64_e32 v[22:23], v[4:5]
	v_mov_b64_e32 v[20:21], v[2:3]
	v_mov_b64_e32 v[18:19], v[0:1]
	v_mov_b64_e32 v[16:17], v[14:15]
	s_mov_b32 s10, 0
	v_mul_f32_e32 v188, 0x42000000, v127
	v_mov_b32_e32 v131, v130
	v_add_u32_e32 v189, s59, v145
	v_subrev_u32_e32 v190, s76, v177
	v_mov_b32_e32 v191, 0
	v_mov_b32_e32 v133, 0xff800000
	s_mov_b32 s76, 0
	s_mov_b32 s77, 0
	v_mov_b64_e32 v[14:15], v[12:13]
	v_mov_b64_e32 v[12:13], v[10:11]
	v_mov_b64_e32 v[10:11], v[8:9]
	v_mov_b64_e32 v[8:9], v[6:7]
	v_mov_b64_e32 v[6:7], v[4:5]
	v_mov_b64_e32 v[4:5], v[2:3]
	v_mov_b64_e32 v[2:3], v[0:1]
	s_mov_b32 s80, 0
	s_mov_b32 s81, 0
	v_mov_b32_e32 v244, v127
	v_fma_f32 v226, 0, v127, v130
	v_add_f32_e32 v227, v130, v127
	v_pk_fma_f32 v[228:229], v[244:245], s[22:23], v[130:131] op_sel_hi:[0,1,1]
	v_pk_fma_f32 v[230:231], v[244:245], s[24:25], v[130:131] op_sel_hi:[0,1,1]
	v_pk_fma_f32 v[232:233], v[244:245], s[26:27], v[130:131] op_sel_hi:[0,1,1]
	v_pk_fma_f32 v[234:235], v[244:245], s[28:29], v[130:131] op_sel_hi:[0,1,1]
	v_pk_fma_f32 v[236:237], v[244:245], s[30:31], v[130:131] op_sel_hi:[0,1,1]
	v_pk_fma_f32 v[238:239], v[244:245], s[34:35], v[130:131] op_sel_hi:[0,1,1]
	v_pk_fma_f32 v[240:241], v[244:245], s[36:37], v[130:131] op_sel_hi:[0,1,1]
	v_add_u32_e32 v137, s76, v190
	v_add_u32_e32 v137, 64, v137
	v_cvt_f32_i32_e32 v137, v137
.La_top:
	v_add_f32_e32 v66, 0x427c0000, v137
	s_mov_b64 s[2:3], exec
	v_mul_f32_e32 v120, v127, v66
	v_pk_add_f32 v[142:143], v[132:133], v[120:121]
	s_nop 0
	v_cmp_lt_f32_e32 vcc, v142, v143
	s_and_saveexec_b64 s[4:5], s[0:1]
	s_cbranch_execz .La_flag_done
	s_cmp_eq_u64 vcc, s[2:3]
	s_cselect_b64 s[2:3], -1, 0
	v_cndmask_b32_e64 v66, 0, 1, s[2:3]
	s_and_b32 s2, s81, 2
	s_lshl_b32 s2, s2, 4
	s_add_i32 s2, s74, s2
	v_mov_b32_e32 v67, s2
	ds_write_b32 v67, v66

; #define LAS __attribute__((address_space(3)))
; __device__ __forceinline__ int crow(int r, int hi) { return (r & 3) + 8 * (r >> 2) + 4 * hi; }
; __device__ __forceinline__ float ex2(float v) { return __builtin_amdgcn_exp2f(v); }
; #define MFMA32(a, b, c) __builtin_amdgcn_mfma_f32_32x32x16_bf16((a), (b), (c), 0, 0, 0)
; __device__ __forceinline__ void unit(LAS unsigned char* lds, bf16_t* P1, const bf16_t* vaT, int b, int h, int qblk, float lam, const float* subln_w, const float* khalf) {
;     ...
;         const LAS unsigned char* kb = lds + stg * STG;
;         stg = (stg + 1) & 3;
;         f32x16 S0, S1;
;         { float slv = sl2; asm volatile("" : "+v"(slv));
; #pragma unroll
;           for (int r = 0; r < 16; ++r) { S0[r] = __builtin_fmaf(slv, (float)((r & 3) + 8 * (r >> 2)), sl2h); S1[r] = S0[r]; } }
; #pragma unroll
;         for (int ks = 0; ks < 4; ++ks) {
;             const bf16x8 a0 = *(const LAS bf16x8*)(kb + koff[ks]);
;             const bf16x8 a1 = *(const LAS bf16x8*)(kb + koff[ks] + 32 * 256);
;             S0 = MFMA32(a0, qf[ks], S0); S1 = MFMA32(a1, qf[ks], S1);
;         }
;         const int kv0 = 64 * j;
;         if (j >= NT - 2) {
; #pragma unroll
;             for (int r = 0; r < 16; ++r) { const int kv = kv0 + crow(r, hi); if (kv > qrow) S0[r] = -INFINITY; if (kv + 32 > qrow) S1[r] = -INFINITY; }
;         }
;         const float tb0 = sl2 * (float)(kv0 - qrow), tb1 = tb0 + sl2 * 32.f;
;         float mx0 = S0[0], mx1 = S1[0];
; #pragma unroll
;         for (int r = 1; r < 16; ++r) { mx0 = fmaxf(mx0, S0[r]); mx1 = fmaxf(mx1, S1[r]); }
;         float mt = fmaxf(mx0 + tb0, mx1 + tb1); mt = fmaxf(mt, __shfl_xor(mt, 32));
;         const bool skip = __all((mt < m - 24.f) || (mt == -INFINITY));
;         if (!skip) {
;         const float mn = fmaxf(m, mt); const float alpha = ex2(m - mn); m = mn;
;         const float c0 = tb0 - mn, c1 = tb1 - mn;
;         f32x2 ps2 = (f32x2){0.f, 0.f};
; #pragma unroll
;         for (int r = 0; r < 16; r += 2) { f32x2 a = (f32x2){S0[r], S0[r + 1]} + c0, bq = (f32x2){S1[r], S1[r + 1]} + c1;
;             a.x = ex2(a.x); a.y = ex2(a.y); bq.x = ex2(bq.x); bq.y = ex2(bq.y); S0[r] = a.x; S0[r + 1] = a.y; S1[r] = bq.x; S1[r + 1] = bq.y; ps2 = ps2 + a; ps2 = ps2 + bq; }
;         l = l * alpha + (ps2.x + ps2.y);
;         if (__any(alpha != 1.f)) {
.La_noflagrd:
	v_add3_u32 v201, s82, v129, v151
	v_add3_u32 v135, s82, v185, v151
	v_add3_u32 v249, s82, v186, v151
	v_add3_u32 v254, s82, v187, v151
	ds_read_b128 v[192:195], v201
	ds_read_b128 v[202:205], v135
	ds_read_b128 v[210:213], v249
	ds_read_b128 v[218:221], v254
	ds_read_b128 v[196:199], v201 offset:8192
	ds_read_b128 v[206:209], v135 offset:8192
	ds_read_b128 v[214:217], v249 offset:8192
	ds_read_b128 v[222:225], v254 offset:8192
	s_waitcnt lgkmcnt(8)
	v_add3_u32 v66, v66, v67, v68
	v_add3_u32 v69, v69, v70, v71
	v_add_u32_e32 v72, v72, v73
	v_add3_u32 v66, v66, v69, v72
	v_cmp_eq_u32_e32 vcc, 8, v66
	s_cbranch_vccnz .LBB0_420
.La_nochk:
	s_cmp_lt_u32 s81, 2
	s_cbranch_scc1 .La_qk_nodmaA
	s_add_i32 s5, s81, 2
	s_cmp_ge_u32 s5, s73
	s_cbranch_scc1 .La_qk_nodmaA
	s_add_i32 s5, s82, 0x10000
	s_and_b32 s5, s5, 0x18000
	s_add_i32 s5, s72, s5
	s_mov_b32 m0, s5
	s_waitcnt lgkmcnt(4)
	v_mfma_f32_32x32x16_bf16 v[82:97], v[192:195], v[98:101], v[226:241]
	global_load_lds_dwordx4 v[140:141], off
	s_add_i32 m0, s5, 0x400
	v_add_u32_e32 v244, s82, v168
	v_add_u32_e32 v245, s82, v169
	v_mfma_f32_32x32x16_bf16 v[82:97], v[202:205], v[102:105], v[82:97]
	global_load_lds_dwordx4 v[138:139], off
	s_add_i32 m0, s5, 0x4000
	v_add_u32_e32 v246, s82, v170
	v_add_u32_e32 v247, s82, v171
	v_mfma_f32_32x32x16_bf16 v[82:97], v[210:213], v[106:109], v[82:97]
	global_load_lds_dwordx4 v134, s[44:45]
	s_add_i32 m0, s5, 0x4400
	v_add_f32_e32 v143, v133, v121
	v_fma_f32 v248, v127, v137, v188
	v_mfma_f32_32x32x16_bf16 v[82:97], v[218:221], v[110:113], v[82:97]
	global_load_lds_dwordx4 v136, s[44:45]
	s_waitcnt lgkmcnt(0)
	v_mfma_f32_32x32x16_bf16 v[66:81], v[196:199], v[98:101], v[226:241]
	s_add_u32 s44, s44, 0xffffff80
	s_addc_u32 s45, s45, -1
	v_lshl_add_u64 v[138:139], v[138:139], 0, s[38:39]
	v_lshl_add_u64 v[140:141], v[140:141], 0, s[38:39]
	v_mfma_f32_32x32x16_bf16 v[66:81], v[206:209], v[102:105], v[66:81]
	v_max3_f32 v0, v82, v83, v84
	v_max3_f32 v0, v0, v85, v86
	v_mfma_f32_32x32x16_bf16 v[66:81], v[214:217], v[106:109], v[66:81]
	v_max3_f32 v0, v0, v87, v88
	v_max3_f32 v0, v0, v89, v90
	v_max3_f32 v0, v0, v91, v92
	v_mfma_f32_32x32x16_bf16 v[66:81], v[222:225], v[110:113], v[66:81]
	v_max3_f32 v0, v0, v93, v94
	v_max3_f32 v0, v0, v95, v96
	v_max_f32_e32 v0, v0, v97
.La_qk_doneA:
	ds_read_b128 v[192:195], v244 offset:16384
	ds_read_b128 v[196:199], v244 offset:20480
	ds_read_b128 v[202:205], v244 offset:24576
	ds_read_b128 v[206:209], v244 offset:28672
	ds_read_b128 v[210:213], v245 offset:16384
	ds_read_b128 v[214:217], v245 offset:20480
	ds_read_b128 v[218:221], v245 offset:24576
	ds_read_b128 v[222:225], v245 offset:28672
	s_cmp_eq_u32 s81, 0
	s_cbranch_scc1 .La_maskA
.La_nomaskA:
	v_fmac_f32_e32 v0, v127, v137
	s_nop 1
	v_max3_f32 v120, v66, v67, v68
	v_max3_f32 v120, v120, v69, v70
	v_max3_f32 v120, v120, v71, v72
	v_max3_f32 v120, v120, v73, v74
	v_max3_f32 v120, v120, v75, v76
	v_max3_f32 v120, v120, v77, v78
	v_max3_f32 v120, v120, v79, v80
	v_max_f32_e32 v120, v120, v81
	v_add_f32_e32 v120, v248, v120
	v_max_f32_e32 v0, v0, v120
	v_mov_b32_e32 v120, v0
	s_nop 1
	v_permlane32_swap_b32_e32 v0, v120
	v_max_f32_e32 v0, v0, v120
	v_cmp_lt_f32_e32 vcc, v0, v143
	v_cmp_eq_f32_e64 s[4:5], v0, v184
	s_or_b64 s[4:5], vcc, s[4:5]
	s_cmp_eq_u64 s[4:5], exec
	s_cbranch_scc1 .La_skipA
	v_max_f32_e32 v255, v133, v0
	v_mul_f32_e32 v142, v127, v137
	v_sub_f32_e32 v0, v133, v255
	v_exp_f32_e32 v0, v0
	v_sub_f32_e32 v142, v142, v255
	v_sub_f32_e32 v248, v248, v255
	v_cmp_neq_f32_e32 vcc, 1.0, v0
	s_cbranch_vccnz .La_rescaleA

; #define LAS __attribute__((address_space(3)))
; __device__ __forceinline__ int crow(int r, int hi) { return (r & 3) + 8 * (r >> 2) + 4 * hi; }
; __device__ __forceinline__ float ex2(float v) { return __builtin_amdgcn_exp2f(v); }
; #define MFMA32(a, b, c) __builtin_amdgcn_mfma_f32_32x32x16_bf16((a), (b), (c), 0, 0, 0)
; __device__ __forceinline__ void unit(LAS unsigned char* lds, bf16_t* P1, const bf16_t* vaT, int b, int h, int qblk, float lam, const float* subln_w, const float* khalf) {
;     ...
;         if (jj + 3 < NT) { DMA_TILE(j - 3, (stg + 3) & 3); }
;         const LAS unsigned char* kb = lds + stg * STG;
;         stg = (stg + 1) & 3;
;         f32x16 S0, S1;
;         { float slv = sl2; asm volatile("" : "+v"(slv));
; #pragma unroll
;           for (int r = 0; r < 16; ++r) { S0[r] = __builtin_fmaf(slv, (float)((r & 3) + 8 * (r >> 2)), sl2h); S1[r] = S0[r]; } }
; #pragma unroll
;         for (int ks = 0; ks < 4; ++ks) {
;             const bf16x8 a0 = *(const LAS bf16x8*)(kb + koff[ks]);
;             const bf16x8 a1 = *(const LAS bf16x8*)(kb + koff[ks] + 32 * 256);
;             S0 = MFMA32(a0, qf[ks], S0); S1 = MFMA32(a1, qf[ks], S1);
;         }
;         const int kv0 = 64 * j;
;         if (j >= NT - 2) {
; #pragma unroll
;             for (int r = 0; r < 16; ++r) { const int kv = kv0 + crow(r, hi); if (kv > qrow) S0[r] = -INFINITY; if (kv + 32 > qrow) S1[r] = -INFINITY; }
;         }
;         const float tb0 = sl2 * (float)(kv0 - qrow), tb1 = tb0 + sl2 * 32.f;
;         float mx0 = S0[0], mx1 = S1[0];
; #pragma unroll
;         for (int r = 1; r < 16; ++r) { mx0 = fmaxf(mx0, S0[r]); mx1 = fmaxf(mx1, S1[r]); }
;         float mt = fmaxf(mx0 + tb0, mx1 + tb1); mt = fmaxf(mt, __shfl_xor(mt, 32));
;         const bool skip = __all((mt < m - 24.f) || (mt == -INFINITY));
;         if (!skip) {
;         const float mn = fmaxf(m, mt); const float alpha = ex2(m - mn); m = mn;
;         const float c0 = tb0 - mn, c1 = tb1 - mn;
;         f32x2 ps2 = (f32x2){0.f, 0.f};
; #pragma unroll
;         for (int r = 0; r < 16; r += 2) { f32x2 a = (f32x2){S0[r], S0[r + 1]} + c0, bq = (f32x2){S1[r], S1[r + 1]} + c1;
;             a.x = ex2(a.x); a.y = ex2(a.y); bq.x = ex2(bq.x); bq.y = ex2(bq.y); S0[r] = a.x; S0[r + 1] = a.y; S1[r] = bq.x; S1[r + 1] = bq.y; ps2 = ps2 + a; ps2 = ps2 + bq; }
;         l = l * alpha + (ps2.x + ps2.y);
;         if (__any(alpha != 1.f)) {
.La_endA:
	ds_read_b128 v[192:195], v201 offset:32768
	ds_read_b128 v[202:205], v135 offset:32768
	ds_read_b128 v[210:213], v249 offset:32768
	ds_read_b128 v[218:221], v254 offset:32768
	ds_read_b128 v[196:199], v201 offset:40960
	ds_read_b128 v[206:209], v135 offset:40960
	ds_read_b128 v[214:217], v249 offset:40960
	ds_read_b128 v[222:225], v254 offset:40960
	s_add_i32 s5, s81, 3
	s_cmp_ge_u32 s5, s73
	s_cbranch_scc1 .La_qk_nodmaB
	s_add_i32 s5, s82, 0x18000
	s_and_b32 s5, s5, 0x18000
	s_add_i32 s5, s72, s5
	s_mov_b32 m0, s5
	s_waitcnt lgkmcnt(4)
	v_mfma_f32_32x32x16_bf16 v[82:97], v[192:195], v[98:101], v[226:241]
	global_load_lds_dwordx4 v[140:141], off
	s_add_i32 m0, s5, 0x400
	v_add_f32_e32 v142, 0xc2800000, v137
	v_add_f32_e32 v143, v255, v121
	v_mfma_f32_32x32x16_bf16 v[82:97], v[202:205], v[102:105], v[82:97]
	global_load_lds_dwordx4 v[138:139], off
	s_add_i32 m0, s5, 0x4000
	v_fma_f32 v248, v127, v142, v188
	v_mfma_f32_32x32x16_bf16 v[82:97], v[210:213], v[106:109], v[82:97]
	global_load_lds_dwordx4 v134, s[44:45]
	s_add_i32 m0, s5, 0x4400
	v_mfma_f32_32x32x16_bf16 v[82:97], v[218:221], v[110:113], v[82:97]
	global_load_lds_dwordx4 v136, s[44:45]
	s_waitcnt lgkmcnt(0)
	v_mfma_f32_32x32x16_bf16 v[66:81], v[196:199], v[98:101], v[226:241]
	s_add_u32 s44, s44, 0xffffff80
	s_addc_u32 s45, s45, -1
	v_lshl_add_u64 v[138:139], v[138:139], 0, s[38:39]
	v_lshl_add_u64 v[140:141], v[140:141], 0, s[38:39]
	v_mfma_f32_32x32x16_bf16 v[66:81], v[206:209], v[102:105], v[66:81]
	v_max3_f32 v0, v82, v83, v84
	v_max3_f32 v0, v0, v85, v86
	v_mfma_f32_32x32x16_bf16 v[66:81], v[214:217], v[106:109], v[66:81]
	v_max3_f32 v0, v0, v87, v88
	v_max3_f32 v0, v0, v89, v90
	v_max3_f32 v0, v0, v91, v92
	v_mfma_f32_32x32x16_bf16 v[66:81], v[222:225], v[110:113], v[66:81]
	v_max3_f32 v0, v0, v93, v94
	v_max3_f32 v0, v0, v95, v96
	v_max_f32_e32 v0, v0, v97
.La_qk_doneB:
	ds_read_b128 v[192:195], v244 offset:49152
	ds_read_b128 v[196:199], v244 offset:53248
	ds_read_b128 v[202:205], v244 offset:57344
	ds_read_b128 v[206:209], v244 offset:61440
	ds_read_b128 v[210:213], v245 offset:49152
	ds_read_b128 v[214:217], v245 offset:53248
	ds_read_b128 v[218:221], v245 offset:57344
	ds_read_b128 v[222:225], v245 offset:61440
	s_cmp_eq_u32 s81, 0
	s_cbranch_scc1 .La_maskB
.La_nomaskB:
	v_fmac_f32_e32 v0, v127, v142
	s_nop 1
	v_max3_f32 v120, v66, v67, v68
	v_max3_f32 v120, v120, v69, v70
	v_max3_f32 v120, v120, v71, v72
	v_max3_f32 v120, v120, v73, v74
	v_max3_f32 v120, v120, v75, v76
	v_max3_f32 v120, v120, v77, v78
	v_max3_f32 v120, v120, v79, v80
	v_max_f32_e32 v120, v120, v81
	v_add_f32_e32 v120, v248, v120
	v_max_f32_e32 v0, v0, v120
	v_mov_b32_e32 v120, v0
	s_nop 1
	v_permlane32_swap_b32_e32 v0, v120
	v_max_f32_e32 v0, v0, v120
	v_cmp_lt_f32_e32 vcc, v0, v143
	v_cmp_eq_f32_e64 s[4:5], v0, v184
	s_or_b64 s[4:5], vcc, s[4:5]
	s_cmp_eq_u64 s[4:5], exec
	s_cbranch_scc1 .La_skipB
	v_max_f32_e32 v133, v255, v0
	v_mul_f32_e32 v142, v127, v142
	v_sub_f32_e32 v0, v255, v133
	v_exp_f32_e32 v0, v0
	v_sub_f32_e32 v142, v142, v133
	v_sub_f32_e32 v248, v248, v133
	v_cmp_neq_f32_e32 vcc, 1.0, v0
	s_cbranch_vccnz .La_rescaleB
; #define LAS __attribute__((address_space(3)))
; __device__ __forceinline__ unsigned cvtpk(float lo, float hi) { return pg8::cvt_pk_bf16(lo, hi); }
; __device__ __forceinline__ float ex2(float v) { return __builtin_amdgcn_exp2f(v); }
; #define MFMA32(a, b, c) __builtin_amdgcn_mfma_f32_32x32x16_bf16((a), (b), (c), 0, 0, 0)
; __device__ __forceinline__ void unit(LAS unsigned char* lds, bf16_t* P1, const bf16_t* vaT, int b, int h, int qblk, float lam, const float* subln_w, const float* khalf) {
;     ...
;         const float mn = fmaxf(m, mt); const float alpha = ex2(m - mn); m = mn;
;         const float c0 = tb0 - mn, c1 = tb1 - mn;
;         f32x2 ps2 = (f32x2){0.f, 0.f};
; #pragma unroll
;         for (int r = 0; r < 16; r += 2) { f32x2 a = (f32x2){S0[r], S0[r + 1]} + c0, bq = (f32x2){S1[r], S1[r + 1]} + c1;
;             a.x = ex2(a.x); a.y = ex2(a.y); bq.x = ex2(bq.x); bq.y = ex2(bq.y); S0[r] = a.x; S0[r + 1] = a.y; S1[r] = bq.x; S1[r + 1] = bq.y; ps2 = ps2 + a; ps2 = ps2 + bq; }
;         l = l * alpha + (ps2.x + ps2.y);
;         if (__any(alpha != 1.f)) {
; #pragma unroll
;             for (int d = 0; d < 4; ++d) O[d] = O[d] * alpha;
;         }
;         u32x4 pk[2][2];
; #pragma unroll
;         for (int s = 0; s < 2; ++s) {
;             pk[0][s] = (u32x4){cvtpk(S0[8 * s + 0], S0[8 * s + 1]), cvtpk(S0[8 * s + 2], S0[8 * s + 3]), cvtpk(S0[8 * s + 4], S0[8 * s + 5]), cvtpk(S0[8 * s + 6], S0[8 * s + 7])};
;             pk[1][s] = (u32x4){cvtpk(S1[8 * s + 0], S1[8 * s + 1]), cvtpk(S1[8 * s + 2], S1[8 * s + 3]), cvtpk(S1[8 * s + 4], S1[8 * s + 5]), cvtpk(S1[8 * s + 6], S1[8 * s + 7])};
;         }
; #pragma unroll
;         for (int d = 0; d < 4; ++d)
; #pragma unroll
;             for (int t2 = 0; t2 < 2; ++t2)
; #pragma unroll
;                 for (int s = 0; s < 2; ++s) {
;                     const bf16x8 vf = *(const LAS bf16x8*)(kb + voff[2 * t2 + s] + d * 32 * 128);
;                     O[d] = MFMA32(vf, __builtin_bit_cast(bf16x8, pk[t2][s]), O[d]);
;                 }
;         }
.La_norescaleB:
	v_pk_add_f32 v[82:83], v[82:83], v[142:143] op_sel_hi:[1,0]
	v_pk_add_f32 v[84:85], v[84:85], v[142:143] op_sel_hi:[1,0]
	v_pk_add_f32 v[86:87], v[86:87], v[142:143] op_sel_hi:[1,0]
	v_pk_add_f32 v[88:89], v[88:89], v[142:143] op_sel_hi:[1,0]
	v_exp_f32_e32 v82, v82
	v_exp_f32_e32 v83, v83
	v_exp_f32_e32 v84, v84
	v_exp_f32_e32 v85, v85
	v_exp_f32_e32 v86, v86
	v_exp_f32_e32 v87, v87
	v_exp_f32_e32 v88, v88
	v_exp_f32_e32 v89, v89
	v_pk_add_f32 v[252:253], v[82:83], v[84:85]
	v_cvt_pk_bf16_f32 v82, v82, v83
	v_cvt_pk_bf16_f32 v83, v84, v85
	v_cvt_pk_bf16_f32 v84, v86, v87
	v_cvt_pk_bf16_f32 v85, v88, v89
	v_pk_add_f32 v[252:253], v[252:253], v[86:87]
	v_pk_add_f32 v[252:253], v[252:253], v[88:89]
	s_waitcnt lgkmcnt(0)
	v_mfma_f32_32x32x16_bf16 v[50:65], v[192:195], v[82:85], v[50:65]
	ds_read_b128 v[192:195], v246 offset:49152
	v_pk_add_f32 v[90:91], v[90:91], v[142:143] op_sel_hi:[1,0]
	v_pk_add_f32 v[92:93], v[92:93], v[142:143] op_sel_hi:[1,0]
	v_pk_add_f32 v[94:95], v[94:95], v[142:143] op_sel_hi:[1,0]
	v_pk_add_f32 v[96:97], v[96:97], v[142:143] op_sel_hi:[1,0]
	v_exp_f32_e32 v90, v90
	v_mfma_f32_32x32x16_bf16 v[34:49], v[196:199], v[82:85], v[34:49]
	ds_read_b128 v[196:199], v246 offset:53248
	v_exp_f32_e32 v91, v91
	v_exp_f32_e32 v92, v92
	v_exp_f32_e32 v93, v93
	v_exp_f32_e32 v94, v94
	v_exp_f32_e32 v95, v95
	v_mfma_f32_32x32x16_bf16 v[18:33], v[202:205], v[82:85], v[18:33]
	ds_read_b128 v[202:205], v246 offset:57344
	v_exp_f32_e32 v96, v96
	v_exp_f32_e32 v97, v97
	v_pk_add_f32 v[252:253], v[252:253], v[90:91]
	v_pk_add_f32 v[252:253], v[252:253], v[92:93]
	v_cvt_pk_bf16_f32 v90, v90, v91
	v_mfma_f32_32x32x16_bf16 v[2:17], v[206:209], v[82:85], v[2:17]
	ds_read_b128 v[206:209], v246 offset:61440
	v_cvt_pk_bf16_f32 v91, v92, v93
	v_cvt_pk_bf16_f32 v92, v94, v95
	v_cvt_pk_bf16_f32 v93, v96, v97
	v_pk_add_f32 v[252:253], v[252:253], v[94:95]
	v_pk_add_f32 v[252:253], v[252:253], v[96:97]
	v_mfma_f32_32x32x16_bf16 v[50:65], v[210:213], v[90:93], v[50:65]
	ds_read_b128 v[210:213], v247 offset:49152
	v_pk_add_f32 v[66:67], v[66:67], v[248:249] op_sel_hi:[1,0]
	v_pk_add_f32 v[68:69], v[68:69], v[248:249] op_sel_hi:[1,0]
	v_pk_add_f32 v[70:71], v[70:71], v[248:249] op_sel_hi:[1,0]
	v_pk_add_f32 v[72:73], v[72:73], v[248:249] op_sel_hi:[1,0]
	v_exp_f32_e32 v66, v66
	v_mfma_f32_32x32x16_bf16 v[34:49], v[214:217], v[90:93], v[34:49]
	ds_read_b128 v[214:217], v247 offset:53248
	v_exp_f32_e32 v67, v67
	v_exp_f32_e32 v68, v68
	v_exp_f32_e32 v69, v69
	v_exp_f32_e32 v70, v70
	v_exp_f32_e32 v71, v71
	v_mfma_f32_32x32x16_bf16 v[18:33], v[218:221], v[90:93], v[18:33]
	ds_read_b128 v[218:221], v247 offset:57344
	v_exp_f32_e32 v72, v72
	v_exp_f32_e32 v73, v73
	v_pk_add_f32 v[252:253], v[252:253], v[66:67]
	v_pk_add_f32 v[252:253], v[252:253], v[68:69]
	v_cvt_pk_bf16_f32 v66, v66, v67
	v_mfma_f32_32x32x16_bf16 v[2:17], v[222:225], v[90:93], v[2:17]
	ds_read_b128 v[222:225], v247 offset:61440
	v_cvt_pk_bf16_f32 v67, v68, v69
	v_cvt_pk_bf16_f32 v68, v70, v71
	v_cvt_pk_bf16_f32 v69, v72, v73
	v_pk_add_f32 v[252:253], v[252:253], v[70:71]
	v_pk_add_f32 v[252:253], v[252:253], v[72:73]
	s_waitcnt lgkmcnt(4)
	v_mfma_f32_32x32x16_bf16 v[50:65], v[192:195], v[66:69], v[50:65]
	v_pk_add_f32 v[74:75], v[74:75], v[248:249] op_sel_hi:[1,0]
	v_pk_add_f32 v[76:77], v[76:77], v[248:249] op_sel_hi:[1,0]
	v_pk_add_f32 v[78:79], v[78:79], v[248:249] op_sel_hi:[1,0]
	v_pk_add_f32 v[80:81], v[80:81], v[248:249] op_sel_hi:[1,0]
	v_exp_f32_e32 v74, v74
	v_mfma_f32_32x32x16_bf16 v[34:49], v[196:199], v[66:69], v[34:49]
	v_exp_f32_e32 v75, v75
	v_exp_f32_e32 v76, v76
	v_exp_f32_e32 v77, v77
	v_exp_f32_e32 v78, v78
	v_exp_f32_e32 v79, v79
	v_mfma_f32_32x32x16_bf16 v[18:33], v[202:205], v[66:69], v[18:33]
	v_exp_f32_e32 v80, v80
	v_exp_f32_e32 v81, v81
	v_pk_add_f32 v[252:253], v[252:253], v[74:75]
	v_pk_add_f32 v[252:253], v[252:253], v[76:77]
	v_cvt_pk_bf16_f32 v74, v74, v75
	v_mfma_f32_32x32x16_bf16 v[2:17], v[206:209], v[66:69], v[2:17]
	v_cvt_pk_bf16_f32 v75, v76, v77
	v_cvt_pk_bf16_f32 v76, v78, v79
	v_cvt_pk_bf16_f32 v77, v80, v81
	v_pk_add_f32 v[252:253], v[252:253], v[78:79]
	v_pk_add_f32 v[252:253], v[252:253], v[80:81]
	s_waitcnt lgkmcnt(0)
	v_mfma_f32_32x32x16_bf16 v[50:65], v[210:213], v[74:77], v[50:65]
	v_add_f32_e32 v250, v252, v253
	v_mfma_f32_32x32x16_bf16 v[34:49], v[214:217], v[74:77], v[34:49]
	v_fma_f32 v191, v191, v0, v250
	v_mfma_f32_32x32x16_bf16 v[18:33], v[218:221], v[74:77], v[18:33]
	v_mfma_f32_32x32x16_bf16 v[2:17], v[222:225], v[74:77], v[2:17]
.La_endB:
	s_add_i32 s80, s80, 2
	s_and_b32 s80, s80, 3
	s_add_i32 s4, s59, s76
	s_add_i32 s81, s81, 2
	s_sub_i32 s76, s76, 0x80
	v_add_f32_e32 v137, 0xc3000000, v137
	s_cmp_eq_u32 s4, 0
	s_cbranch_scc0 .La_top
	s_branch .LBB0_420

; #define LAS __attribute__((address_space(3)))
; __device__ __forceinline__ int crow(int r, int hi) { return (r & 3) + 8 * (r >> 2) + 4 * hi; }
; #define MFMA32(a, b, c) __builtin_amdgcn_mfma_f32_32x32x16_bf16((a), (b), (c), 0, 0, 0)
; __device__ __forceinline__ void unit(LAS unsigned char* lds, bf16_t* P1, const bf16_t* vaT, int b, int h, int qblk, float lam, const float* subln_w, const float* khalf) {
;     ...
;         for (int ks = 0; ks < 4; ++ks) {
;             const bf16x8 a0 = *(const LAS bf16x8*)(kb + koff[ks]);
;             const bf16x8 a1 = *(const LAS bf16x8*)(kb + koff[ks] + 32 * 256);
;             S0 = MFMA32(a0, qf[ks], S0); S1 = MFMA32(a1, qf[ks], S1);
;         }
;         const int kv0 = 64 * j;
;         if (j >= NT - 2) {
; #pragma unroll
;             for (int r = 0; r < 16; ++r) { const int kv = kv0 + crow(r, hi); if (kv > qrow) S0[r] = -INFINITY; if (kv + 32 > qrow) S1[r] = -INFINITY; }
;         }
;         const float tb0 = sl2 * (float)(kv0 - qrow), tb1 = tb0 + sl2 * 32.f;
;         float mx0 = S0[0], mx1 = S1[0];
; #pragma unroll
;         for (int r = 1; r < 16; ++r) { mx0 = fmaxf(mx0, S0[r]); mx1 = fmaxf(mx1, S1[r]); }
;         float mt = fmaxf(mx0 + tb0, mx1 + tb1); mt = fmaxf(mt, __shfl_xor(mt, 32));
;         const bool skip = __all((mt < m - 24.f) || (mt == -INFINITY));
.La_qk_nodmaA:
	s_waitcnt lgkmcnt(4)
	v_mfma_f32_32x32x16_bf16 v[82:97], v[192:195], v[98:101], v[226:241]
	v_add_u32_e32 v244, s82, v168
	v_add_u32_e32 v245, s82, v169
	v_mfma_f32_32x32x16_bf16 v[82:97], v[202:205], v[102:105], v[82:97]
	v_add_u32_e32 v246, s82, v170
	v_add_u32_e32 v247, s82, v171
	v_mfma_f32_32x32x16_bf16 v[82:97], v[210:213], v[106:109], v[82:97]
	v_add_f32_e32 v143, v133, v121
	v_fma_f32 v248, v127, v137, v188
	v_mfma_f32_32x32x16_bf16 v[82:97], v[218:221], v[110:113], v[82:97]
	s_waitcnt lgkmcnt(0)
	v_mfma_f32_32x32x16_bf16 v[66:81], v[196:199], v[98:101], v[226:241]
	v_mfma_f32_32x32x16_bf16 v[66:81], v[206:209], v[102:105], v[66:81]
	v_max3_f32 v0, v82, v83, v84
	v_max3_f32 v0, v0, v85, v86
	v_mfma_f32_32x32x16_bf16 v[66:81], v[214:217], v[106:109], v[66:81]
	v_max3_f32 v0, v0, v87, v88
	v_max3_f32 v0, v0, v89, v90
	v_max3_f32 v0, v0, v91, v92
	v_mfma_f32_32x32x16_bf16 v[66:81], v[222:225], v[110:113], v[66:81]
	v_max3_f32 v0, v0, v93, v94
	v_max3_f32 v0, v0, v95, v96
	v_max_f32_e32 v0, v0, v97
	s_branch .La_qk_doneA
.La_maskA:
	s_nop 3
	v_add_u32_e32 v243, s76, v189
	v_add_u32_e32 v250, 0x60, v243
	v_add_u32_e32 v251, 64, v243
	v_cmp_le_i32_e32 vcc, v250, v125
	s_nop 6
	v_cndmask_b32_e32 v66, v184, v66, vcc
	v_cmp_lt_i32_e32 vcc, v251, v125
	s_nop 1
	v_cndmask_b32_e32 v83, v184, v83, vcc
	v_cmp_le_i32_e32 vcc, v251, v125
	v_add_u32_e32 v251, 0x61, v243
	s_nop 0
	v_cndmask_b32_e32 v82, v184, v82, vcc
	v_cmp_le_i32_e32 vcc, v251, v125
	v_add_u32_e32 v251, 0x42, v243
	s_nop 0
	v_cndmask_b32_e32 v67, v184, v67, vcc
	v_cmp_le_i32_e32 vcc, v251, v125
	v_add_u32_e32 v251, 0x62, v243
	s_nop 0
	v_cndmask_b32_e32 v84, v184, v84, vcc
	v_cmp_le_i32_e32 vcc, v251, v125
	v_add_u32_e32 v251, 0x43, v243
	s_nop 0
	v_cndmask_b32_e32 v68, v184, v68, vcc
	v_cmp_le_i32_e32 vcc, v251, v125
	v_add_u32_e32 v251, 0x63, v243
	s_nop 0
	v_cndmask_b32_e32 v85, v184, v85, vcc
	v_cmp_le_i32_e32 vcc, v251, v125
	v_add_u32_e32 v251, 0x48, v243
	s_nop 0
	v_cndmask_b32_e32 v69, v184, v69, vcc
	v_cmp_le_i32_e32 vcc, v251, v125
	v_add_u32_e32 v251, 0x68, v243
	s_nop 0
	v_cndmask_b32_e32 v86, v184, v86, vcc
	v_cmp_le_i32_e32 vcc, v251, v125
	v_add_u32_e32 v251, 0x49, v243
	s_nop 0
	v_cndmask_b32_e32 v70, v184, v70, vcc
	v_cmp_le_i32_e32 vcc, v251, v125
	v_add_u32_e32 v251, 0x69, v243
	s_nop 0
	v_cndmask_b32_e32 v87, v184, v87, vcc
	v_cmp_le_i32_e32 vcc, v251, v125
	v_add_u32_e32 v251, 0x4a, v243
	s_nop 0
	v_cndmask_b32_e32 v71, v184, v71, vcc
	v_cmp_le_i32_e32 vcc, v251, v125
	v_add_u32_e32 v251, 0x6a, v243
	s_nop 0
	v_cndmask_b32_e32 v88, v184, v88, vcc
	v_cmp_le_i32_e32 vcc, v251, v125
	v_add_u32_e32 v251, 0x4b, v243
	s_nop 0
	v_cndmask_b32_e32 v72, v184, v72, vcc
	v_cmp_le_i32_e32 vcc, v251, v125
	v_add_u32_e32 v251, 0x6b, v243
	s_nop 0
	v_cndmask_b32_e32 v89, v184, v89, vcc
	v_cmp_le_i32_e32 vcc, v251, v125
	v_add_u32_e32 v251, 0x50, v243
	s_nop 0
	v_cndmask_b32_e32 v73, v184, v73, vcc
	v_cmp_le_i32_e32 vcc, v251, v125
	v_add_u32_e32 v251, 0x70, v243
	s_nop 0
	v_cndmask_b32_e32 v90, v184, v90, vcc
	v_cmp_le_i32_e32 vcc, v251, v125
	v_add_u32_e32 v251, 0x51, v243
	s_nop 0
	v_cndmask_b32_e32 v74, v184, v74, vcc
	v_cmp_le_i32_e32 vcc, v251, v125
	v_add_u32_e32 v251, 0x71, v243
	s_nop 0
	v_cndmask_b32_e32 v91, v184, v91, vcc
	v_cmp_le_i32_e32 vcc, v251, v125
	v_add_u32_e32 v251, 0x52, v243
	s_nop 0
	v_cndmask_b32_e32 v75, v184, v75, vcc
	v_cmp_le_i32_e32 vcc, v251, v125
	v_add_u32_e32 v251, 0x72, v243
	s_nop 0
	v_cndmask_b32_e32 v92, v184, v92, vcc
	v_cmp_le_i32_e32 vcc, v251, v125
	v_add_u32_e32 v251, 0x53, v243
	s_nop 0
	v_cndmask_b32_e32 v76, v184, v76, vcc
	v_cmp_le_i32_e32 vcc, v251, v125
	v_add_u32_e32 v251, 0x73, v243
	s_nop 0
	v_cndmask_b32_e32 v93, v184, v93, vcc
	v_cmp_le_i32_e32 vcc, v251, v125
	v_add_u32_e32 v251, 0x58, v243
	s_nop 0
	v_cndmask_b32_e32 v77, v184, v77, vcc
	v_cmp_le_i32_e32 vcc, v251, v125
	v_add_u32_e32 v251, 0x78, v243
	s_nop 0
	v_cndmask_b32_e32 v94, v184, v94, vcc
	v_cmp_le_i32_e32 vcc, v251, v125
	v_add_u32_e32 v251, 0x59, v243
	s_nop 0
	v_cndmask_b32_e32 v78, v184, v78, vcc
	v_cmp_le_i32_e32 vcc, v251, v125
	v_add_u32_e32 v251, 0x79, v243
	s_nop 0
	v_cndmask_b32_e32 v95, v184, v95, vcc
	v_cmp_le_i32_e32 vcc, v251, v125
	v_add_u32_e32 v251, 0x5a, v243
	s_nop 0
	v_cndmask_b32_e32 v79, v184, v79, vcc
	v_cmp_le_i32_e32 vcc, v251, v125
	v_add_u32_e32 v251, 0x7a, v243
	s_nop 0
	v_cndmask_b32_e32 v96, v184, v96, vcc
	v_cmp_le_i32_e32 vcc, v251, v125
	v_add_u32_e32 v251, 0x5b, v243
	v_add_u32_e32 v243, 0x7b, v243
	v_cndmask_b32_e32 v80, v184, v80, vcc
	v_cmp_le_i32_e32 vcc, v251, v125
	s_nop 1
	v_cndmask_b32_e32 v97, v184, v97, vcc
	v_cmp_le_i32_e32 vcc, v243, v125
	s_nop 1
	v_cndmask_b32_e32 v81, v184, v81, vcc
	v_max3_f32 v0, v82, v83, v84
	v_max3_f32 v0, v0, v85, v86
	v_max3_f32 v0, v0, v87, v88
	v_max3_f32 v0, v0, v89, v90
	v_max3_f32 v0, v0, v91, v92
	v_max3_f32 v0, v0, v93, v94
	v_max3_f32 v0, v0, v95, v96
	v_max_f32_e32 v0, v0, v97
	s_branch .La_nomaskA
.La_skipA:
	v_mov_b32_e32 v255, v133
	s_branch .La_endA

; #define LAS __attribute__((address_space(3)))
; __device__ __forceinline__ int crow(int r, int hi) { return (r & 3) + 8 * (r >> 2) + 4 * hi; }
; #define MFMA32(a, b, c) __builtin_amdgcn_mfma_f32_32x32x16_bf16((a), (b), (c), 0, 0, 0)
; __device__ __forceinline__ void unit(LAS unsigned char* lds, bf16_t* P1, const bf16_t* vaT, int b, int h, int qblk, float lam, const float* subln_w, const float* khalf) {
;     ...
;         for (int ks = 0; ks < 4; ++ks) {
;             const bf16x8 a0 = *(const LAS bf16x8*)(kb + koff[ks]);
;             const bf16x8 a1 = *(const LAS bf16x8*)(kb + koff[ks] + 32 * 256);
;             S0 = MFMA32(a0, qf[ks], S0); S1 = MFMA32(a1, qf[ks], S1);
;         }
;         const int kv0 = 64 * j;
;         if (j >= NT - 2) {
; #pragma unroll
;             for (int r = 0; r < 16; ++r) { const int kv = kv0 + crow(r, hi); if (kv > qrow) S0[r] = -INFINITY; if (kv + 32 > qrow) S1[r] = -INFINITY; }
;         }
;         const float tb0 = sl2 * (float)(kv0 - qrow), tb1 = tb0 + sl2 * 32.f;
;         float mx0 = S0[0], mx1 = S1[0];
; #pragma unroll
;         for (int r = 1; r < 16; ++r) { mx0 = fmaxf(mx0, S0[r]); mx1 = fmaxf(mx1, S1[r]); }
;         float mt = fmaxf(mx0 + tb0, mx1 + tb1); mt = fmaxf(mt, __shfl_xor(mt, 32));
;         const bool skip = __all((mt < m - 24.f) || (mt == -INFINITY));
.La_qk_nodmaB:
	s_waitcnt lgkmcnt(4)
	v_mfma_f32_32x32x16_bf16 v[82:97], v[192:195], v[98:101], v[226:241]
	v_add_f32_e32 v142, 0xc2800000, v137
	v_add_f32_e32 v143, v255, v121
	v_mfma_f32_32x32x16_bf16 v[82:97], v[202:205], v[102:105], v[82:97]
	v_fma_f32 v248, v127, v142, v188
	v_mfma_f32_32x32x16_bf16 v[82:97], v[210:213], v[106:109], v[82:97]
	v_mfma_f32_32x32x16_bf16 v[82:97], v[218:221], v[110:113], v[82:97]
	s_waitcnt lgkmcnt(0)
	v_mfma_f32_32x32x16_bf16 v[66:81], v[196:199], v[98:101], v[226:241]
	v_mfma_f32_32x32x16_bf16 v[66:81], v[206:209], v[102:105], v[66:81]
	v_max3_f32 v0, v82, v83, v84
	v_max3_f32 v0, v0, v85, v86
	v_mfma_f32_32x32x16_bf16 v[66:81], v[214:217], v[106:109], v[66:81]
	v_max3_f32 v0, v0, v87, v88
	v_max3_f32 v0, v0, v89, v90
	v_max3_f32 v0, v0, v91, v92
	v_mfma_f32_32x32x16_bf16 v[66:81], v[222:225], v[110:113], v[66:81]
	v_max3_f32 v0, v0, v93, v94
	v_max3_f32 v0, v0, v95, v96
	v_max_f32_e32 v0, v0, v97
	s_branch .La_qk_doneB
.La_maskB:
	s_nop 3
	v_add_u32_e32 v243, s100, v189
	v_add_u32_e32 v250, 0x60, v243
	v_add_u32_e32 v251, 64, v243
	v_cmp_le_i32_e32 vcc, v250, v125
	s_nop 6
	v_cndmask_b32_e32 v66, v184, v66, vcc
	v_cmp_lt_i32_e32 vcc, v251, v125
	s_nop 1
	v_cndmask_b32_e32 v83, v184, v83, vcc
	v_cmp_le_i32_e32 vcc, v251, v125
	v_add_u32_e32 v251, 0x61, v243
	s_nop 0
	v_cndmask_b32_e32 v82, v184, v82, vcc
	v_cmp_le_i32_e32 vcc, v251, v125
	v_add_u32_e32 v251, 0x42, v243
	s_nop 0
	v_cndmask_b32_e32 v67, v184, v67, vcc
	v_cmp_le_i32_e32 vcc, v251, v125
	v_add_u32_e32 v251, 0x62, v243
	s_nop 0
	v_cndmask_b32_e32 v84, v184, v84, vcc
	v_cmp_le_i32_e32 vcc, v251, v125
	v_add_u32_e32 v251, 0x43, v243
	s_nop 0
	v_cndmask_b32_e32 v68, v184, v68, vcc
	v_cmp_le_i32_e32 vcc, v251, v125
	v_add_u32_e32 v251, 0x63, v243
	s_nop 0
	v_cndmask_b32_e32 v85, v184, v85, vcc
	v_cmp_le_i32_e32 vcc, v251, v125
	v_add_u32_e32 v251, 0x48, v243
	s_nop 0
	v_cndmask_b32_e32 v69, v184, v69, vcc
	v_cmp_le_i32_e32 vcc, v251, v125
	v_add_u32_e32 v251, 0x68, v243
	s_nop 0
	v_cndmask_b32_e32 v86, v184, v86, vcc
	v_cmp_le_i32_e32 vcc, v251, v125
	v_add_u32_e32 v251, 0x49, v243
	s_nop 0
	v_cndmask_b32_e32 v70, v184, v70, vcc
	v_cmp_le_i32_e32 vcc, v251, v125
	v_add_u32_e32 v251, 0x69, v243
	s_nop 0
	v_cndmask_b32_e32 v87, v184, v87, vcc
	v_cmp_le_i32_e32 vcc, v251, v125
	v_add_u32_e32 v251, 0x4a, v243
	s_nop 0
	v_cndmask_b32_e32 v71, v184, v71, vcc
	v_cmp_le_i32_e32 vcc, v251, v125
	v_add_u32_e32 v251, 0x6a, v243
	s_nop 0
	v_cndmask_b32_e32 v88, v184, v88, vcc
	v_cmp_le_i32_e32 vcc, v251, v125
	v_add_u32_e32 v251, 0x4b, v243
	s_nop 0
	v_cndmask_b32_e32 v72, v184, v72, vcc
	v_cmp_le_i32_e32 vcc, v251, v125
	v_add_u32_e32 v251, 0x6b, v243
	s_nop 0
	v_cndmask_b32_e32 v89, v184, v89, vcc
	v_cmp_le_i32_e32 vcc, v251, v125
	v_add_u32_e32 v251, 0x50, v243
	s_nop 0
	v_cndmask_b32_e32 v73, v184, v73, vcc
	v_cmp_le_i32_e32 vcc, v251, v125
	v_add_u32_e32 v251, 0x70, v243
	s_nop 0
	v_cndmask_b32_e32 v90, v184, v90, vcc
	v_cmp_le_i32_e32 vcc, v251, v125
	v_add_u32_e32 v251, 0x51, v243
	s_nop 0
	v_cndmask_b32_e32 v74, v184, v74, vcc
	v_cmp_le_i32_e32 vcc, v251, v125
	v_add_u32_e32 v251, 0x71, v243
	s_nop 0
	v_cndmask_b32_e32 v91, v184, v91, vcc
	v_cmp_le_i32_e32 vcc, v251, v125
	v_add_u32_e32 v251, 0x52, v243
	s_nop 0
	v_cndmask_b32_e32 v75, v184, v75, vcc
	v_cmp_le_i32_e32 vcc, v251, v125
	v_add_u32_e32 v251, 0x72, v243
	s_nop 0
	v_cndmask_b32_e32 v92, v184, v92, vcc
	v_cmp_le_i32_e32 vcc, v251, v125
	v_add_u32_e32 v251, 0x53, v243
	s_nop 0
	v_cndmask_b32_e32 v76, v184, v76, vcc
	v_cmp_le_i32_e32 vcc, v251, v125
	v_add_u32_e32 v251, 0x73, v243
	s_nop 0
	v_cndmask_b32_e32 v93, v184, v93, vcc
	v_cmp_le_i32_e32 vcc, v251, v125
	v_add_u32_e32 v251, 0x58, v243
	s_nop 0
	v_cndmask_b32_e32 v77, v184, v77, vcc
	v_cmp_le_i32_e32 vcc, v251, v125
	v_add_u32_e32 v251, 0x78, v243
	s_nop 0
	v_cndmask_b32_e32 v94, v184, v94, vcc
	v_cmp_le_i32_e32 vcc, v251, v125
	v_add_u32_e32 v251, 0x59, v243
	s_nop 0
	v_cndmask_b32_e32 v78, v184, v78, vcc
	v_cmp_le_i32_e32 vcc, v251, v125
	v_add_u32_e32 v251, 0x79, v243
	s_nop 0
	v_cndmask_b32_e32 v95, v184, v95, vcc
	v_cmp_le_i32_e32 vcc, v251, v125
	v_add_u32_e32 v251, 0x5a, v243
	s_nop 0
	v_cndmask_b32_e32 v79, v184, v79, vcc
	v_cmp_le_i32_e32 vcc, v251, v125
	v_add_u32_e32 v251, 0x7a, v243
	s_nop 0
	v_cndmask_b32_e32 v96, v184, v96, vcc
	v_cmp_le_i32_e32 vcc, v251, v125
	v_add_u32_e32 v251, 0x5b, v243
	v_add_u32_e32 v243, 0x7b, v243
	v_cndmask_b32_e32 v80, v184, v80, vcc
	v_cmp_le_i32_e32 vcc, v251, v125
	s_nop 1
	v_cndmask_b32_e32 v97, v184, v97, vcc
	v_cmp_le_i32_e32 vcc, v243, v125
	s_nop 1
	v_cndmask_b32_e32 v81, v184, v81, vcc
	v_max3_f32 v0, v82, v83, v84
	v_max3_f32 v0, v0, v85, v86
	v_max3_f32 v0, v0, v87, v88
	v_max3_f32 v0, v0, v89, v90
	v_max3_f32 v0, v0, v91, v92
	v_max3_f32 v0, v0, v93, v94
	v_max3_f32 v0, v0, v95, v96
	v_max_f32_e32 v0, v0, v97
	s_branch .La_nomaskB
.La_skipB:
	v_mov_b32_e32 v133, v255
	s_branch .La_endB
